# strategy 4 mirrored: one static s_setprio 1 for waves 0-3 across the MLA and NA phase
# baseline (speedup 1.0000x reference)
.LBB0_1348:
	s_or_b64 exec, exec, s[0:1]
	v_readlane_b32 s0, v246, 5
	s_and_b32 s3, s2, 7
	s_ashr_i32 s21, s0, 3
	s_ashr_i32 s20, s2, 3
	s_mul_i32 s0, s3, s21
	s_add_i32 s28, s0, s20
	s_cmpk_gt_i32 s28, 0x3ff
	s_waitcnt lgkmcnt(0)
	s_barrier
	v_readlane_b32 s1, v246, 6
	s_cbranch_scc1 .LBB0_1382
	v_readfirstlane_b32 s98, v162
	s_nop 3
	s_cmp_ge_u32 s98, 0x100
	s_cbranch_scc1 .Lp7_prio_done
	s_setprio 1
